# speedup vs baseline: 1.0165x; 1.0038x over previous
; #define SCHED() __builtin_amdgcn_sched_barrier(0)
; #define GLOADS(KS, VS, t, slot) do { char* lb_ = shm + (slot) * 16384 + wid * 1024;                                  \
;     __builtin_amdgcn_global_load_lds((const unsigned*)((KS) + (size_t)(t) * 64 * PW), (unsigned*)(lb_), 16, 0, 0);    \
;     __builtin_amdgcn_global_load_lds((const unsigned*)((VS) + (t) * 64), (unsigned*)(lb_ + 8192), 16, 0, 0); } while (0)
; #define PART(P0, P1) do { _Pragma("unroll") for (int r = 0; r < 16; ++r) FMK(P0[r]);                             \
;     _Pragma("unroll") for (int r = 0; r < 16; ++r) FMK(P1[r]);                                                    \
;     _Pragma("unroll") for (int r = 0; r < 16; ++r) P0[r] = __builtin_amdgcn_exp2f(P0[r]); } while (0)
; #define EXP1(P1) do { _Pragma("unroll") for (int r = 0; r < 16; ++r) P1[r] = __builtin_amdgcn_exp2f(P1[r]); } while (0)
; #define PACK(P0, P1) do { float ps_ = 0.f; _Pragma("unroll") for (int r = 0; r < 16; ++r) ps_ += P0[r] + P1[r]; lsum += ps_;  \
;     PK4(P0, 0, pa0); PK4(P0, 8, pa1); PK4(P1, 0, pa2); PK4(P1, 8, pa3); } while (0)
; #define KFR(slot) do { const char* Kc = shm + (slot) * 16384;                                                      \
;     _Pragma("unroll") for (int d0 = 0; d0 < 4; ++d0) { fr_[d0 * 2] = *(const bf16x8*)(Kc + roff[d0]); fr_[d0 * 2 + 1] = *(const bf16x8*)(Kc + roff[d0] + 4096); } } while (0)
; #define VFR(slot) do { const char* Vc = shm + (slot) * 16384 + 8192;                                               \
;     _Pragma("unroll") for (int ks = 0; ks < 4; ++ks) { fr_[ks * 2] = *(const bf16x8*)(Vc + roff[ks]); fr_[ks * 2 + 1] = *(const bf16x8*)(Vc + roff[ks] + 4096); } } while (0)
; #define PVM() do { PV1(pa0, 0); PV1(pa1, 1); PV1(pa2, 2); PV1(pa3, 3); } while (0)
; __device__ __forceinline__ void gqa_items(const Params& p, int l, int L, char* shm, const int tid, const int local, const int G, const int nGQ) {
;     ...
;     for (int j = 0; j < NT; ++j) {
;       if (j + 2 < NT) { const int ns_ = (cur == 0) ? 2 : cur - 1; GLOADS(Ks, Vs, j + 2, ns_); }
;       SCHED(); KFR(cur); SCHED();
;       QKT(pA0, pA1); SCHED();
;       PART(pA0, pA1); EXP1(pA1); SCHED();
;       VFR(cur); SCHED();
;       PACK(pA0, pA1); SCHED();
;       PVM();
.Lgq_step:
	ds_read_b128 v[192:195], v224
	ds_read_b128 v[196:199], v224 offset:4096
	ds_read_b128 v[200:203], v225
	ds_read_b128 v[204:207], v225 offset:4096
	ds_read_b128 v[208:211], v226
	ds_read_b128 v[212:215], v226 offset:4096
	ds_read_b128 v[216:219], v227
	ds_read_b128 v[220:223], v227 offset:4096
	s_add_i32 s2, s15, 2
	s_cmp_ge_u32 s2, s96
	s_cbranch_scc1 .Lgq_nold
	s_add_i32 s2, s14, 2
	s_and_b32 s2, s2, 3
	s_lshl_b32 s2, s2, 14
	s_add_i32 s2, s7, s2
	s_mov_b32 m0, s2
	v_lshl_add_u64 v[228:229], s[58:59], 1, v[74:75]
	global_load_lds_dwordx4 v[78:79], off
	s_add_i32 m0, s2, 0x2000
	s_nop 0
	global_load_lds_dwordx4 v[228:229], off
	v_lshl_add_u64 v[78:79], v[78:79], 0, s[92:93]
	s_add_i32 s58, s58, 64
	s_add_i32 s2, s14, 3
	s_and_b32 s2, s2, 3
	s_lshl_b32 s2, s2, 14
	s_add_i32 s2, s7, s2
	s_mov_b32 m0, s2
	v_lshl_add_u64 v[228:229], s[58:59], 1, v[74:75]
	global_load_lds_dwordx4 v[78:79], off
	s_add_i32 m0, s2, 0x2000
	s_nop 0
	global_load_lds_dwordx4 v[228:229], off
	v_lshl_add_u64 v[78:79], v[78:79], 0, s[92:93]
	s_add_i32 s58, s58, 64
.Lgq_nold:
	s_waitcnt lgkmcnt(7)
	v_mfma_f32_32x32x16_bf16 v[34:49], v[192:195], v[50:53], 0
	ds_read_b128 v[144:147], v224 offset:8192
	s_waitcnt lgkmcnt(7)
	v_mfma_f32_32x32x16_bf16 v[128:143], v[196:199], v[50:53], 0
	ds_read_b128 v[148:151], v224 offset:12288
	s_waitcnt lgkmcnt(7)
	v_mfma_f32_32x32x16_bf16 v[34:49], v[200:203], v[54:57], v[34:49]
	ds_read_b128 v[152:155], v225 offset:8192
	s_waitcnt lgkmcnt(7)
	v_mfma_f32_32x32x16_bf16 v[128:143], v[204:207], v[54:57], v[128:143]
	ds_read_b128 v[156:159], v225 offset:12288
	s_waitcnt lgkmcnt(7)
	v_mfma_f32_32x32x16_bf16 v[34:49], v[208:211], v[58:61], v[34:49]
	ds_read_b128 v[160:163], v226 offset:8192
	s_waitcnt lgkmcnt(7)
	v_mfma_f32_32x32x16_bf16 v[128:143], v[212:215], v[58:61], v[128:143]
	ds_read_b128 v[164:167], v226 offset:12288
	s_waitcnt lgkmcnt(7)
	v_mfma_f32_32x32x16_bf16 v[34:49], v[216:219], v[62:65], v[34:49]
	ds_read_b128 v[168:171], v227 offset:8192
	s_waitcnt lgkmcnt(7)
	v_mfma_f32_32x32x16_bf16 v[128:143], v[220:223], v[62:65], v[128:143]
	ds_read_b128 v[172:175], v227 offset:12288
	s_add_i32 s3, s14, 1
	s_and_b32 s3, s3, 3
	s_lshl_b32 s3, s3, 14
	v_add_u32_e32 v230, s3, v109
	v_add_u32_e32 v231, s3, v120
	v_add_u32_e32 v232, s3, v121
	v_add_u32_e32 v233, s3, v122
	s_waitcnt lgkmcnt(4)
	ds_read_b128 v[192:195], v230
	ds_read_b128 v[196:199], v230 offset:4096
	ds_read_b128 v[200:203], v231
	ds_read_b128 v[204:207], v231 offset:4096
	ds_read_b128 v[208:211], v232
	ds_read_b128 v[212:215], v232 offset:4096
	ds_read_b128 v[216:219], v233
	ds_read_b128 v[220:223], v233 offset:4096
	v_fmamk_f32 v34, v34, 0x3e38aa3b, v71
	v_fmamk_f32 v35, v35, 0x3e38aa3b, v71
	v_fmamk_f32 v36, v36, 0x3e38aa3b, v71
	v_fmamk_f32 v37, v37, 0x3e38aa3b, v71
	v_fmamk_f32 v38, v38, 0x3e38aa3b, v71
	v_fmamk_f32 v39, v39, 0x3e38aa3b, v71
	v_fmamk_f32 v40, v40, 0x3e38aa3b, v71
	v_fmamk_f32 v41, v41, 0x3e38aa3b, v71
	v_fmamk_f32 v42, v42, 0x3e38aa3b, v71
	v_fmamk_f32 v43, v43, 0x3e38aa3b, v71
	v_fmamk_f32 v44, v44, 0x3e38aa3b, v71
	v_fmamk_f32 v45, v45, 0x3e38aa3b, v71
	v_fmamk_f32 v46, v46, 0x3e38aa3b, v71
	v_fmamk_f32 v47, v47, 0x3e38aa3b, v71
	v_fmamk_f32 v48, v48, 0x3e38aa3b, v71
	v_fmamk_f32 v49, v49, 0x3e38aa3b, v71
	v_exp_f32_e32 v34, v34
	v_exp_f32_e32 v35, v35
	v_exp_f32_e32 v36, v36
	v_exp_f32_e32 v37, v37
	v_exp_f32_e32 v38, v38
	v_exp_f32_e32 v39, v39
	v_exp_f32_e32 v40, v40
	v_exp_f32_e32 v41, v41
	v_exp_f32_e32 v42, v42
	v_exp_f32_e32 v43, v43
	v_exp_f32_e32 v44, v44
	v_exp_f32_e32 v45, v45
	v_exp_f32_e32 v46, v46
	v_exp_f32_e32 v47, v47
	v_exp_f32_e32 v48, v48
	v_exp_f32_e32 v49, v49
	v_cvt_pk_bf16_f32 v176, v34, v35
	v_cvt_pk_bf16_f32 v177, v36, v37
	v_cvt_pk_bf16_f32 v178, v38, v39
	v_cvt_pk_bf16_f32 v179, v40, v41
	v_cvt_pk_bf16_f32 v180, v42, v43
	v_cvt_pk_bf16_f32 v181, v44, v45
	v_cvt_pk_bf16_f32 v182, v46, v47
	v_cvt_pk_bf16_f32 v183, v48, v49
	v_permlane32_swap_b32_e32 v176, v178
	v_permlane32_swap_b32_e32 v177, v179
	v_permlane32_swap_b32_e32 v180, v182
	v_permlane32_swap_b32_e32 v181, v183
	s_waitcnt lgkmcnt(8)
	v_mfma_f32_32x32x16_bf16 v[18:33], v[176:179], v[144:147], v[18:33]
	v_fmamk_f32 v128, v128, 0x3e38aa3b, v71
	v_fmamk_f32 v129, v129, 0x3e38aa3b, v71
	v_fmamk_f32 v130, v130, 0x3e38aa3b, v71
	v_fmamk_f32 v131, v131, 0x3e38aa3b, v71
	v_fmamk_f32 v132, v132, 0x3e38aa3b, v71
	v_fmamk_f32 v133, v133, 0x3e38aa3b, v71
	v_fmamk_f32 v134, v134, 0x3e38aa3b, v71
	v_fmamk_f32 v135, v135, 0x3e38aa3b, v71
	v_mfma_f32_32x32x16_bf16 v[2:17], v[176:179], v[148:151], v[2:17]
	v_fmamk_f32 v136, v136, 0x3e38aa3b, v71
	v_fmamk_f32 v137, v137, 0x3e38aa3b, v71
	v_fmamk_f32 v138, v138, 0x3e38aa3b, v71
	v_fmamk_f32 v139, v139, 0x3e38aa3b, v71
	v_fmamk_f32 v140, v140, 0x3e38aa3b, v71
	v_fmamk_f32 v141, v141, 0x3e38aa3b, v71
	v_fmamk_f32 v142, v142, 0x3e38aa3b, v71
	v_fmamk_f32 v143, v143, 0x3e38aa3b, v71
	v_mfma_f32_32x32x16_bf16 v[18:33], v[180:183], v[152:155], v[18:33]
	v_exp_f32_e32 v128, v128
	v_exp_f32_e32 v129, v129
	v_exp_f32_e32 v130, v130
	v_exp_f32_e32 v131, v131
	v_exp_f32_e32 v132, v132
	v_exp_f32_e32 v133, v133
	v_exp_f32_e32 v134, v134
	v_exp_f32_e32 v135, v135
	v_mfma_f32_32x32x16_bf16 v[2:17], v[180:183], v[156:159], v[2:17]
	v_exp_f32_e32 v136, v136
	v_exp_f32_e32 v137, v137
	v_exp_f32_e32 v138, v138
	v_exp_f32_e32 v139, v139
	v_exp_f32_e32 v140, v140
	v_exp_f32_e32 v141, v141
	v_exp_f32_e32 v142, v142
	v_exp_f32_e32 v143, v143
	v_cvt_pk_bf16_f32 v184, v128, v129
	v_cvt_pk_bf16_f32 v185, v130, v131
	v_cvt_pk_bf16_f32 v186, v132, v133
	v_cvt_pk_bf16_f32 v187, v134, v135
	v_cvt_pk_bf16_f32 v188, v136, v137
	v_cvt_pk_bf16_f32 v189, v138, v139
; #define SCHED() __builtin_amdgcn_sched_barrier(0)
; #define PART(P0, P1) do { _Pragma("unroll") for (int r = 0; r < 16; ++r) FMK(P0[r]);                             \
;     _Pragma("unroll") for (int r = 0; r < 16; ++r) FMK(P1[r]);                                                    \
;     _Pragma("unroll") for (int r = 0; r < 16; ++r) P0[r] = __builtin_amdgcn_exp2f(P0[r]); } while (0)
; #define EXP1(P1) do { _Pragma("unroll") for (int r = 0; r < 16; ++r) P1[r] = __builtin_amdgcn_exp2f(P1[r]); } while (0)
; #define PACK(P0, P1) do { float ps_ = 0.f; _Pragma("unroll") for (int r = 0; r < 16; ++r) ps_ += P0[r] + P1[r]; lsum += ps_;  \
;     PK4(P0, 0, pa0); PK4(P0, 8, pa1); PK4(P1, 0, pa2); PK4(P1, 8, pa3); } while (0)
; #define VFR(slot) do { const char* Vc = shm + (slot) * 16384 + 8192;                                               \
;     _Pragma("unroll") for (int ks = 0; ks < 4; ++ks) { fr_[ks * 2] = *(const bf16x8*)(Vc + roff[ks]); fr_[ks * 2 + 1] = *(const bf16x8*)(Vc + roff[ks] + 4096); } } while (0)
; #define QKT(P0, P1) do { _Pragma("unroll") for (int r = 0; r < 16; ++r) { P0[r] = 0.f; P1[r] = 0.f; }              \
;     _Pragma("unroll") for (int d0 = 0; d0 < 4; ++d0) { P0 = __builtin_amdgcn_mfma_f32_32x32x16_bf16(fr_[d0 * 2], qr[d0], P0, 0, 0, 0);     \
;       P1 = __builtin_amdgcn_mfma_f32_32x32x16_bf16(fr_[d0 * 2 + 1], qr[d0], P1, 0, 0, 0); } } while (0)
; #define PVM() do { PV1(pa0, 0); PV1(pa1, 1); PV1(pa2, 2); PV1(pa3, 3); } while (0)
; __device__ __forceinline__ void gqa_items(const Params& p, int l, int L, char* shm, const int tid, const int local, const int G, const int nGQ) {
;     ...
;       QKT(pA0, pA1); SCHED();
;       PART(pA0, pA1); EXP1(pA1); SCHED();
;       VFR(cur); SCHED();
;       PACK(pA0, pA1); SCHED();
;       PVM();
	v_cvt_pk_bf16_f32 v190, v140, v141
	v_cvt_pk_bf16_f32 v191, v142, v143
	v_permlane32_swap_b32_e32 v184, v186
	v_permlane32_swap_b32_e32 v185, v187
	v_permlane32_swap_b32_e32 v188, v190
	v_permlane32_swap_b32_e32 v189, v191
	v_add_f32_e32 v34, v34, v128
	v_add_f32_e32 v35, v35, v129
	v_mfma_f32_32x32x16_bf16 v[18:33], v[184:187], v[160:163], v[18:33]
	v_add_f32_e32 v36, v36, v130
	v_add_f32_e32 v37, v37, v131
	v_add_f32_e32 v38, v38, v132
	v_add_f32_e32 v39, v39, v133
	v_add_f32_e32 v40, v40, v134
	v_add_f32_e32 v41, v41, v135
	v_add_f32_e32 v42, v42, v136
	v_add_f32_e32 v43, v43, v137
	v_mfma_f32_32x32x16_bf16 v[2:17], v[184:187], v[164:167], v[2:17]
	v_add_f32_e32 v44, v44, v138
	v_add_f32_e32 v45, v45, v139
	v_add_f32_e32 v46, v46, v140
	v_add_f32_e32 v47, v47, v141
	v_add_f32_e32 v48, v48, v142
	v_add_f32_e32 v49, v49, v143
	v_add_f32_e32 v35, v35, v34
	v_add_f32_e32 v36, v36, v35
	v_mfma_f32_32x32x16_bf16 v[18:33], v[188:191], v[168:171], v[18:33]
	v_add_f32_e32 v37, v37, v36
	v_add_f32_e32 v38, v38, v37
	v_add_f32_e32 v39, v39, v38
	v_add_f32_e32 v40, v40, v39
	v_add_f32_e32 v41, v41, v40
	v_add_f32_e32 v42, v42, v41
	v_add_f32_e32 v43, v43, v42
	v_add_f32_e32 v44, v44, v43
	v_mfma_f32_32x32x16_bf16 v[2:17], v[188:191], v[172:175], v[2:17]
	v_add_f32_e32 v45, v45, v44
	v_add_f32_e32 v46, v46, v45
	v_add_f32_e32 v47, v47, v46
	v_add_f32_e32 v48, v48, v47
	v_add_f32_e32 v49, v49, v48
	v_add_f32_e32 v127, v127, v49
	s_waitcnt lgkmcnt(0)
	v_mfma_f32_32x32x16_bf16 v[34:49], v[192:195], v[50:53], 0
	ds_read_b128 v[144:147], v230 offset:8192
	v_mfma_f32_32x32x16_bf16 v[128:143], v[196:199], v[50:53], 0
	ds_read_b128 v[148:151], v230 offset:12288
	v_mfma_f32_32x32x16_bf16 v[34:49], v[200:203], v[54:57], v[34:49]
	ds_read_b128 v[152:155], v231 offset:8192
	v_mfma_f32_32x32x16_bf16 v[128:143], v[204:207], v[54:57], v[128:143]
	ds_read_b128 v[156:159], v231 offset:12288
	v_mfma_f32_32x32x16_bf16 v[34:49], v[208:211], v[58:61], v[34:49]
	ds_read_b128 v[160:163], v232 offset:8192
	v_mfma_f32_32x32x16_bf16 v[128:143], v[212:215], v[58:61], v[128:143]
	ds_read_b128 v[164:167], v232 offset:12288
	v_mfma_f32_32x32x16_bf16 v[34:49], v[216:219], v[62:65], v[34:49]
	ds_read_b128 v[168:171], v233 offset:8192
	v_mfma_f32_32x32x16_bf16 v[128:143], v[220:223], v[62:65], v[128:143]
	ds_read_b128 v[172:175], v233 offset:12288
	s_add_i32 s0, s14, 2
	s_and_b32 s0, s0, 3
	s_lshl_b32 s16, s0, 14
	v_add_u32_e32 v224, s16, v109
	v_add_u32_e32 v225, s16, v120
	v_add_u32_e32 v226, s16, v121
	v_add_u32_e32 v227, s16, v122
	s_nop 1
	v_fmamk_f32 v34, v34, 0x3e38aa3b, v71
	v_fmamk_f32 v35, v35, 0x3e38aa3b, v71
	v_fmamk_f32 v36, v36, 0x3e38aa3b, v71
	v_fmamk_f32 v37, v37, 0x3e38aa3b, v71
	v_fmamk_f32 v38, v38, 0x3e38aa3b, v71
	v_fmamk_f32 v39, v39, 0x3e38aa3b, v71
	v_fmamk_f32 v40, v40, 0x3e38aa3b, v71
	v_fmamk_f32 v41, v41, 0x3e38aa3b, v71
	v_fmamk_f32 v42, v42, 0x3e38aa3b, v71
	v_fmamk_f32 v43, v43, 0x3e38aa3b, v71
	v_fmamk_f32 v44, v44, 0x3e38aa3b, v71
	v_fmamk_f32 v45, v45, 0x3e38aa3b, v71
	v_fmamk_f32 v46, v46, 0x3e38aa3b, v71
	v_fmamk_f32 v47, v47, 0x3e38aa3b, v71
	v_fmamk_f32 v48, v48, 0x3e38aa3b, v71
	v_fmamk_f32 v49, v49, 0x3e38aa3b, v71
	v_exp_f32_e32 v34, v34
	v_exp_f32_e32 v35, v35
	v_exp_f32_e32 v36, v36
	v_exp_f32_e32 v37, v37
	v_exp_f32_e32 v38, v38
	v_exp_f32_e32 v39, v39
	v_exp_f32_e32 v40, v40
	v_exp_f32_e32 v41, v41
	v_exp_f32_e32 v42, v42
	v_exp_f32_e32 v43, v43
	v_exp_f32_e32 v44, v44
	v_exp_f32_e32 v45, v45
	v_exp_f32_e32 v46, v46
	v_exp_f32_e32 v47, v47
	v_exp_f32_e32 v48, v48
	v_exp_f32_e32 v49, v49
	v_cvt_pk_bf16_f32 v176, v34, v35
	v_cvt_pk_bf16_f32 v177, v36, v37
	v_cvt_pk_bf16_f32 v178, v38, v39
	v_cvt_pk_bf16_f32 v179, v40, v41
	v_cvt_pk_bf16_f32 v180, v42, v43
	v_cvt_pk_bf16_f32 v181, v44, v45
	v_cvt_pk_bf16_f32 v182, v46, v47
	v_cvt_pk_bf16_f32 v183, v48, v49
	v_permlane32_swap_b32_e32 v176, v178
	v_permlane32_swap_b32_e32 v177, v179
	v_permlane32_swap_b32_e32 v180, v182
	v_permlane32_swap_b32_e32 v181, v183
	s_waitcnt lgkmcnt(0)
; #define SCHED() __builtin_amdgcn_sched_barrier(0)
; #define PART(P0, P1) do { _Pragma("unroll") for (int r = 0; r < 16; ++r) FMK(P0[r]);                             \
;     _Pragma("unroll") for (int r = 0; r < 16; ++r) FMK(P1[r]);                                                    \
;     _Pragma("unroll") for (int r = 0; r < 16; ++r) P0[r] = __builtin_amdgcn_exp2f(P0[r]); } while (0)
; #define EXP1(P1) do { _Pragma("unroll") for (int r = 0; r < 16; ++r) P1[r] = __builtin_amdgcn_exp2f(P1[r]); } while (0)
; #define PACK(P0, P1) do { float ps_ = 0.f; _Pragma("unroll") for (int r = 0; r < 16; ++r) ps_ += P0[r] + P1[r]; lsum += ps_;  \
;     PK4(P0, 0, pa0); PK4(P0, 8, pa1); PK4(P1, 0, pa2); PK4(P1, 8, pa3); } while (0)
; #define VFR(slot) do { const char* Vc = shm + (slot) * 16384 + 8192;                                               \
;     _Pragma("unroll") for (int ks = 0; ks < 4; ++ks) { fr_[ks * 2] = *(const bf16x8*)(Vc + roff[ks]); fr_[ks * 2 + 1] = *(const bf16x8*)(Vc + roff[ks] + 4096); } } while (0)
; #define PVM() do { PV1(pa0, 0); PV1(pa1, 1); PV1(pa2, 2); PV1(pa3, 3); } while (0)
; __device__ __forceinline__ void gqa_items(const Params& p, int l, int L, char* shm, const int tid, const int local, const int G, const int nGQ) {
;     ...
;       PART(pA0, pA1); EXP1(pA1); SCHED();
;       VFR(cur); SCHED();
;       PACK(pA0, pA1); SCHED();
;       PVM();
;       SCHED();
;       if (j + 2 < NT) asm volatile("s_waitcnt vmcnt(2) lgkmcnt(0)" ::: "memory"); else asm volatile("s_waitcnt vmcnt(0) lgkmcnt(0)" ::: "memory");
;       __builtin_amdgcn_s_barrier(); asm volatile("" ::: "memory"); SCHED();
;       cur = (cur == 2) ? 0 : cur + 1;
;     }
	v_mfma_f32_32x32x16_bf16 v[18:33], v[176:179], v[144:147], v[18:33]
	v_fmamk_f32 v128, v128, 0x3e38aa3b, v71
	v_fmamk_f32 v129, v129, 0x3e38aa3b, v71
	v_fmamk_f32 v130, v130, 0x3e38aa3b, v71
	v_fmamk_f32 v131, v131, 0x3e38aa3b, v71
	v_fmamk_f32 v132, v132, 0x3e38aa3b, v71
	v_fmamk_f32 v133, v133, 0x3e38aa3b, v71
	v_fmamk_f32 v134, v134, 0x3e38aa3b, v71
	v_fmamk_f32 v135, v135, 0x3e38aa3b, v71
	v_mfma_f32_32x32x16_bf16 v[2:17], v[176:179], v[148:151], v[2:17]
	v_fmamk_f32 v136, v136, 0x3e38aa3b, v71
	v_fmamk_f32 v137, v137, 0x3e38aa3b, v71
	v_fmamk_f32 v138, v138, 0x3e38aa3b, v71
	v_fmamk_f32 v139, v139, 0x3e38aa3b, v71
	v_fmamk_f32 v140, v140, 0x3e38aa3b, v71
	v_fmamk_f32 v141, v141, 0x3e38aa3b, v71
	v_fmamk_f32 v142, v142, 0x3e38aa3b, v71
	v_fmamk_f32 v143, v143, 0x3e38aa3b, v71
	v_mfma_f32_32x32x16_bf16 v[18:33], v[180:183], v[152:155], v[18:33]
	v_exp_f32_e32 v128, v128
	v_exp_f32_e32 v129, v129
	v_exp_f32_e32 v130, v130
	v_exp_f32_e32 v131, v131
	v_exp_f32_e32 v132, v132
	v_exp_f32_e32 v133, v133
	v_exp_f32_e32 v134, v134
	v_exp_f32_e32 v135, v135
	v_mfma_f32_32x32x16_bf16 v[2:17], v[180:183], v[156:159], v[2:17]
	v_exp_f32_e32 v136, v136
	v_exp_f32_e32 v137, v137
	v_exp_f32_e32 v138, v138
	v_exp_f32_e32 v139, v139
	v_exp_f32_e32 v140, v140
	v_exp_f32_e32 v141, v141
	v_exp_f32_e32 v142, v142
	v_exp_f32_e32 v143, v143
	v_cvt_pk_bf16_f32 v184, v128, v129
	v_cvt_pk_bf16_f32 v185, v130, v131
	v_cvt_pk_bf16_f32 v186, v132, v133
	v_cvt_pk_bf16_f32 v187, v134, v135
	v_cvt_pk_bf16_f32 v188, v136, v137
	v_cvt_pk_bf16_f32 v189, v138, v139
	v_cvt_pk_bf16_f32 v190, v140, v141
	v_cvt_pk_bf16_f32 v191, v142, v143
	v_permlane32_swap_b32_e32 v184, v186
	v_permlane32_swap_b32_e32 v185, v187
	v_permlane32_swap_b32_e32 v188, v190
	v_permlane32_swap_b32_e32 v189, v191
	v_add_f32_e32 v34, v34, v128
	v_add_f32_e32 v35, v35, v129
	v_mfma_f32_32x32x16_bf16 v[18:33], v[184:187], v[160:163], v[18:33]
	v_add_f32_e32 v36, v36, v130
	v_add_f32_e32 v37, v37, v131
	v_add_f32_e32 v38, v38, v132
	v_add_f32_e32 v39, v39, v133
	v_add_f32_e32 v40, v40, v134
	v_add_f32_e32 v41, v41, v135
	v_add_f32_e32 v42, v42, v136
	v_add_f32_e32 v43, v43, v137
	v_mfma_f32_32x32x16_bf16 v[2:17], v[184:187], v[164:167], v[2:17]
	v_add_f32_e32 v44, v44, v138
	v_add_f32_e32 v45, v45, v139
	v_add_f32_e32 v46, v46, v140
	v_add_f32_e32 v47, v47, v141
	v_add_f32_e32 v48, v48, v142
	v_add_f32_e32 v49, v49, v143
	v_add_f32_e32 v35, v35, v34
	v_add_f32_e32 v36, v36, v35
	v_mfma_f32_32x32x16_bf16 v[18:33], v[188:191], v[168:171], v[18:33]
	v_add_f32_e32 v37, v37, v36
	v_add_f32_e32 v38, v38, v37
	v_add_f32_e32 v39, v39, v38
	v_add_f32_e32 v40, v40, v39
	v_add_f32_e32 v41, v41, v40
	v_add_f32_e32 v42, v42, v41
	v_add_f32_e32 v43, v43, v42
	v_add_f32_e32 v44, v44, v43
	v_mfma_f32_32x32x16_bf16 v[2:17], v[188:191], v[172:175], v[2:17]
	v_add_f32_e32 v45, v45, v44
	v_add_f32_e32 v46, v46, v45
	v_add_f32_e32 v47, v47, v46
	v_add_f32_e32 v48, v48, v47
	v_add_f32_e32 v49, v49, v48
	v_add_f32_e32 v127, v127, v49
	s_mov_b32 s14, s0
	s_add_i32 s15, s15, 2
	s_waitcnt vmcnt(0) lgkmcnt(0)
	s_barrier
	s_cmp_lt_u32 s15, s96
	s_cbranch_scc1 .Lgq_step
